# v034: v032 + mini (sample-row) GEMM unit: row sum-of-squares load issued at unit start instead of load+wait in the epilogue
# baseline (speedup 1.0000x reference)
.LBB0_927:
	s_abs_i32 s1, s28
	s_mul_hi_u32 s14, s1, s62
	v_mov_b32_e32 v33, v214
	s_mul_i32 s15, s14, s74
	s_sub_i32 s1, s1, s15
	v_readfirstlane_b32 s44, v33
	s_bfe_u32 s45, s44, 0x20006
	s_ashr_i32 s50, s44, 8
	s_ashr_i32 s0, s28, 31
	s_add_i32 s15, s14, 1
	s_sub_i32 s20, s1, s74
	s_cmp_ge_u32 s1, s74
	s_cselect_b32 s14, s15, s14
	s_cselect_b32 s1, s20, s1
	s_add_i32 s15, s14, 1
	s_cmp_ge_u32 s1, s74
	s_cselect_b32 s1, s15, s14
	s_xor_b32 s1, s1, s0
	s_sub_i32 s0, s1, s0
	s_mul_i32 s1, s0, s74
	s_lshl_b32 s0, s0, 6
	v_ashrrev_i32_e32 v34, 5, v33
	s_lshl_b32 s51, s45, 4
	v_add_u32_e32 v0, s0, v34
	s_sub_i32 s14, s28, s1
	s_or_b32 s15, s0, s51
	v_ashrrev_i32_e32 v3, 31, v0
	v_mad_u64_u32 v[0:1], s[0:1], v0, s71, 0
	v_mov_b32_e32 v2, v1
	v_mad_u64_u32 v[2:3], s[0:1], v3, s71, v[2:3]
	v_mov_b32_e32 v1, v2
	v_lshlrev_b32_e32 v2, 3, v33
	v_and_b32_e32 v32, 0xf8, v2
	v_lshl_add_u64 v[0:1], v[0:1], 1, s[6:7]
	v_lshlrev_b32_e32 v192, 1, v32
	s_lshl_b32 s0, s14, 6
	v_lshl_add_u64 v[68:69], v[0:1], 0, v[192:193]
	v_add_u32_e32 v0, s0, v34
	v_ashrrev_i32_e32 v3, 31, v0
	v_mad_u64_u32 v[0:1], s[20:21], v0, s71, 0
	v_mov_b32_e32 v2, v1
	v_readlane_b32 s52, v253, 8
	v_mad_u64_u32 v[2:3], s[20:21], v3, s71, v[2:3]
	v_readlane_b32 s58, v253, 14
	v_readlane_b32 s59, v253, 15
	v_mov_b32_e32 v1, v2
	s_mov_b64 s[30:31], s[58:59]
	v_lshl_add_u64 v[0:1], v[0:1], 1, s[10:11]
	v_lshl_add_u64 v[70:71], v[0:1], 0, v[192:193]
	global_load_dwordx4 v[0:3], v[68:69], off
	global_load_dwordx4 v[4:7], v[70:71], off
	s_lshl_b32 s20, s60, 1
	s_mov_b32 s21, s83
	v_lshl_add_u64 v[8:9], v[68:69], 0, s[20:21]
	global_load_dwordx4 v[8:11], v[8:9], off
	v_lshl_add_u64 v[12:13], v[70:71], 0, s[20:21]
	s_lshl_b32 s40, s61, 1
	s_mov_b32 s41, s83
	global_load_dwordx4 v[12:15], v[12:13], off
	v_lshl_add_u64 v[16:17], v[68:69], 0, s[40:41]
	global_load_dwordx4 v[16:19], v[16:17], off
	v_lshl_add_u64 v[20:21], v[70:71], 0, s[40:41]
	global_load_dwordx4 v[20:23], v[20:21], off
	v_lshl_add_u64 v[24:25], v[68:69], 0, s[36:37]
	global_load_dwordx4 v[24:27], v[24:25], off
	v_lshl_add_u64 v[28:29], v[70:71], 0, s[36:37]
	global_load_dwordx4 v[28:31], v[28:29], off
	v_readlane_b32 s53, v253, 9
	s_movk_i32 s1, 0x108
	v_and_b32_e32 v74, 15, v33
	v_and_b32_e32 v51, 63, v33
	v_bfe_u32 v35, v33, 4, 2
	v_mad_u64_u32 v[32:33], s[52:53], v34, s1, v[32:33]
	v_lshl_add_u32 v75, v32, 1, 0
	s_waitcnt lgkmcnt(0)
	s_barrier
	s_add_i32 s1, s15, 0x4000
	v_or_b32_e32 v48, s1, v74
	s_ashr_i32 s1, s0, 31
	v_lshlrev_b32_e32 v192, 3, v35
	v_mov_b32_e32 v52, 0
	v_mul_u32_u24_e32 v76, 0x210, v74
	v_ashrrev_i32_e32 v49, 31, v48
	v_lshlrev_b32_e32 v50, 2, v35
	v_lshlrev_b64 v[244:245], 6, v[48:49]
	v_lshl_add_u64 v[244:245], s[30:31], 0, v[244:245]
	v_lshlrev_b32_e32 v246, 2, v50
	v_mov_b32_e32 v247, 0
	v_lshl_add_u64 v[244:245], v[244:245], 0, v[246:247]
	s_mov_b64 s[52:53], 0x5d00000
	v_lshl_add_u64 v[244:245], v[244:245], 0, s[52:53]
	global_load_dwordx4 v[244:247], v[244:245], off
	s_movk_i32 s82, 0x100
	v_mov_b32_e32 v53, v52
	v_mov_b32_e32 v54, v52
	v_mov_b32_e32 v55, v52
	v_mov_b32_e32 v56, v52
	v_mov_b32_e32 v57, v52
	v_mov_b32_e32 v58, v52
	v_mov_b32_e32 v59, v52
	v_mov_b32_e32 v60, v52
	v_mov_b32_e32 v61, v52
	v_mov_b32_e32 v62, v52
	v_mov_b32_e32 v63, v52
	v_mov_b32_e32 v64, v52
	v_mov_b32_e32 v65, v52
	v_mov_b32_e32 v66, v52
	s_waitcnt vmcnt(0)
	ds_write_b128 v75, v[0:3]
	ds_write_b128 v75, v[4:7] offset:33792
	ds_write_b128 v75, v[8:11] offset:8448
	ds_write_b128 v75, v[12:15] offset:42240
	ds_write_b128 v75, v[16:19] offset:16896
	ds_write_b128 v75, v[20:23] offset:50688
	ds_write_b128 v75, v[24:27] offset:25344
	ds_write_b128 v75, v[28:31] offset:59136
	v_or_b32_e32 v0, s51, v74
	v_mul_u32_u24_e32 v77, 0x210, v0
	v_mov_b64_e32 v[0:1], s[30:31]
	v_mad_i64_i32 v[0:1], s[52:53], v48, s76, v[0:1]
	v_lshl_add_u64 v[0:1], s[0:1], 1, v[0:1]
	s_lshl_b32 s51, s50, 7
	v_lshl_add_u64 v[0:1], v[0:1], 0, v[192:193]
	s_mov_b64 s[52:53], 0x18401800
	s_mov_b32 s1, 2
	v_lshl_add_u64 v[72:73], v[0:1], 0, s[52:53]
	s_mov_b32 s52, 0
	s_lshl_b32 s51, s51, 1
	s_mov_b32 s53, 0
	v_mov_b32_e32 v67, v52
	v_mov_b32_e32 v44, v52
	v_mov_b32_e32 v45, v52
	v_mov_b32_e32 v46, v52
	v_mov_b32_e32 v47, v52
	v_mov_b32_e32 v40, v52
	v_mov_b32_e32 v41, v52
	v_mov_b32_e32 v42, v52
	v_mov_b32_e32 v43, v52
	v_mov_b32_e32 v36, v52
	v_mov_b32_e32 v37, v52
	v_mov_b32_e32 v38, v52
	v_mov_b32_e32 v39, v52
	v_mov_b32_e32 v32, v52
	v_mov_b32_e32 v33, v52
	v_mov_b32_e32 v34, v52
	v_mov_b32_e32 v35, v52
	v_readlane_b32 s54, v253, 10
	v_readlane_b32 s55, v253, 11
	v_readlane_b32 s56, v253, 12
	v_readlane_b32 s57, v253, 13
	s_waitcnt lgkmcnt(0)
	s_barrier
	s_branch .LBB0_929

.LBB0_944:
	v_lshlrev_b64 v[0:1], 6, v[48:49]
	v_lshl_add_u64 v[0:1], s[30:31], 0, v[0:1]
	v_lshlrev_b32_e32 v192, 2, v50
	v_lshl_add_u64 v[0:1], v[0:1], 0, v[192:193]
	v_add_co_u32_e32 v0, vcc, 0x5d00000, v0
	s_nop 1
	v_addc_co_u32_e32 v1, vcc, 0, v1, vcc
	v_mov_b32_e32 v0, v244
	v_mov_b32_e32 v1, v245
	v_mov_b32_e32 v2, v246
	v_mov_b32_e32 v3, v247
	v_cmp_lt_i32_e32 vcc, v223, v218
	s_waitcnt vmcnt(0) lgkmcnt(0)
	v_mov_b32_e32 v22, v1
	v_mov_b32_e32 v23, v2
	v_mov_b32_e32 v1, v3
	v_pk_add_f32 v[0:1], v[22:23], v[0:1]
	s_nop 0
	v_add_f32_e32 v0, v0, v1
	v_cndmask_b32_e32 v1, v217, v223, vcc
	v_lshlrev_b32_e32 v1, 2, v1
	ds_bpermute_b32 v1, v1, v0
	v_cmp_lt_i32_e32 vcc, v224, v218
	s_waitcnt lgkmcnt(0)
	v_add_f32_e32 v0, v0, v1
	v_cndmask_b32_e32 v1, v217, v224, vcc
	v_lshlrev_b32_e32 v1, 2, v1
	ds_bpermute_b32 v1, v1, v0
	s_andn2_b64 vcc, exec, s[2:3]
	s_waitcnt lgkmcnt(0)
	v_add_f32_e32 v0, v0, v1
	v_fmamk_f32 v0, v0, 0x3a800000, v215
	v_rsq_f32_e32 v0, v0
	s_nop 0
	v_mul_f32_e32 v0, s17, v0
	v_pk_mul_f32 v[22:23], v[16:17], v[0:1] op_sel_hi:[1,0]
	v_pk_mul_f32 v[24:25], v[18:19], v[0:1] op_sel_hi:[1,0]
	v_cndmask_b32_e64 v1, 0, 1, s[2:3]
	v_cmp_ne_u32_e64 s[0:1], 1, v1
	s_cbranch_vccnz .LBB0_946
	v_max_f32_e32 v1, v24, v24
	v_max_f32_e32 v2, 0, v1
	v_max_f32_e32 v1, v25, v25
	v_max_f32_e32 v3, 0, v1
	v_max_f32_e32 v1, v22, v22
	v_max_f32_e32 v22, 0, v1
	v_max_f32_e32 v1, v23, v23
	v_max_f32_e32 v23, 0, v1
	v_pk_mul_f32 v[22:23], v[22:23], v[22:23]
	v_pk_mul_f32 v[24:25], v[2:3], v[2:3]
